# scan counted waits + split-K LDS-reduced gemm tails + XCD-aware tile order for the phase-3 GEMM
# speedup vs baseline: 1.0267x; 1.0065x over previous
.LBB0_904:
	s_cmp_lt_i32 s2, 64
	s_cselect_b64 s[4:5], -1, 0
	s_xor_b64 s[6:7], s[24:25], -1
	s_and_b64 s[4:5], s[4:5], s[6:7]
	s_and_b64 vcc, exec, s[4:5]
	s_cbranch_vccnz .LBB0_958
	s_sub_i32 s3, s2, 64
	s_and_b64 s[4:5], s[24:25], exec
	s_cselect_b32 s3, s2, s3
	s_sub_i32 s6, s30, 64
	s_and_b64 s[4:5], s[24:25], exec
	v_mov_b32_e32 v9, v170
	s_cselect_b32 s33, s30, s6
	s_cmpk_gt_i32 s3, 0x107
	v_readfirstlane_b32 s20, v9
	s_cbranch_scc1 .LBB0_919
	v_lshlrev_b32_e32 v0, 4, v9
	v_add_u32_e32 v1, 0x2000, v0
	v_ashrrev_i32_e32 v2, 31, v1
	v_lshrrev_b32_e32 v2, 22, v2
	v_add_u32_e32 v2, v1, v2
	v_ashrrev_i32_e32 v8, 10, v2
	v_mul_i32_i24_e32 v3, 0x400, v8
	v_sub_u32_e32 v1, v1, v3
	v_lshrrev_b32_e32 v3, 4, v1
	v_bitop3_b32 v1, v3, v1, 32 bitop3:0x6c
	v_ashrrev_i32_e32 v3, 31, v1
	v_lshrrev_b32_e32 v3, 26, v3
	v_add_u32_e32 v3, v1, v3
	v_ashrrev_i32_e32 v10, 6, v3
	v_and_b32_e32 v3, 0xc0, v3
	v_sub_u32_e32 v1, v1, v3
	v_mov_b32_e32 v3, 1
	v_lshlrev_b32_e32 v2, 5, v8
	v_ashrrev_i16_sdwa v1, v3, sext(v1) dst_sel:DWORD dst_unused:UNUSED_PAD src0_sel:DWORD src1_sel:BYTE_0
	v_and_b32_e32 v2, 32, v2
	v_bfe_i32 v11, v1, 0, 16
	v_add_u32_e32 v1, v2, v11
	v_lshlrev_b32_e32 v2, 3, v8
	v_and_b32_e32 v2, 0x1ffff0, v2
	v_add_lshl_u32 v2, v10, v2, 11
	v_lshl_add_u32 v140, v1, 1, v2
	v_bfe_i32 v2, v9, 27, 1
	v_lshrrev_b32_e32 v2, 22, v2
	v_add_u32_e32 v2, v0, v2
	v_and_b32_e32 v2, 0xfffffc00, v2
	v_sub_u32_e32 v0, v0, v2
	v_lshrrev_b32_e32 v2, 4, v0
	v_bitop3_b32 v2, v2, v0, 32 bitop3:0x6c
	v_ashrrev_i32_e32 v0, 31, v0
	v_lshrrev_b32_e32 v0, 26, v0
	v_ashrrev_i32_e32 v1, 31, v9
	v_add_u32_e32 v0, v2, v0
	v_lshrrev_b32_e32 v1, 26, v1
	v_ashrrev_i32_e32 v13, 6, v0
	s_load_dwordx2 s[4:5], s[0:1], 0x98
	s_load_dwordx2 s[6:7], s[0:1], 0xb0
	v_add_u32_e32 v1, v9, v1
	v_mul_i32_i24_e32 v0, 64, v13
	v_ashrrev_i32_e32 v12, 6, v1
	v_sub_u32_e32 v0, v2, v0
	v_lshlrev_b32_e32 v1, 5, v12
	v_ashrrev_i16_sdwa v0, v3, sext(v0) dst_sel:DWORD dst_unused:UNUSED_PAD src0_sel:DWORD src1_sel:BYTE_0
	s_mov_b32 s99, s3
	s_mov_b32 s98, s33
	s_cmpk_lg_i32 s33, 0xc0
	s_cbranch_scc1 .Lmy_g1_std
	s_and_b32 s99, s3, 7
	s_mul_i32 s99, s99, 33
	s_lshr_b32 s98, s3, 3
	s_add_i32 s99, s99, s98
	s_movk_i32 s98, 24
.Lmy_g1_std:
	s_ashr_i32 s8, s99, 2
	s_ashr_i32 s18, s20, 6
	v_and_b32_e32 v1, 32, v1
	v_bfe_i32 v14, v0, 0, 16
	s_and_b32 s47, s99, 3
	s_ashr_i32 s9, s8, 31
	s_ashr_i32 s21, s20, 8
	s_lshl_b32 s46, s18, 10
	v_add_u32_e32 v0, v1, v14
	v_lshlrev_b32_e32 v1, 3, v12
	s_waitcnt lgkmcnt(0)
	s_lshl_b64 s[12:13], s[8:9], 19
	s_lshl_b32 s9, s47, 19
	v_and_b32_e32 v1, 0x1ffff0, v1
	s_add_u32 s10, s6, s9
	v_add_lshl_u32 v1, v13, v1, 11
	s_addc_u32 s11, s7, 0
	s_add_i32 s9, s46, 0
	v_lshl_add_u32 v142, v0, 1, v1
	s_add_i32 m0, s9, 0x10000
	v_mov_b32_e32 v145, 0
	global_load_lds_dwordx4 v142, s[10:11]
	s_add_i32 m0, s9, 0x12000
	s_add_u32 s14, s10, 0x40000
	global_load_lds_dwordx4 v140, s[10:11]
	s_addc_u32 s15, s11, 0
	s_add_i32 m0, s9, 0x14000
	v_mov_b32_e32 v143, v145
	global_load_lds_dwordx4 v142, s[14:15]
	s_add_i32 m0, s9, 0x16000
	s_add_u32 s12, s4, s12
	s_addc_u32 s13, s5, s13
	s_add_i32 s48, s9, 0x2000
	global_load_lds_dwordx4 v140, s[14:15]
	s_mov_b32 m0, s9
	s_add_u32 s14, s12, 0x40000
	global_load_lds_dwordx4 v142, s[12:13]
	s_mov_b32 m0, s48
	s_addc_u32 s15, s13, 0
	s_add_i32 s49, s9, 0x4000
	global_load_lds_dwordx4 v140, s[12:13]
	s_mov_b32 m0, s49
	s_add_i32 s50, s9, 0x6000
	global_load_lds_dwordx4 v142, s[14:15]
	s_mov_b32 m0, s50
	v_mov_b32_e32 v141, v145
	global_load_lds_dwordx4 v140, s[14:15]
	s_cmp_eq_u32 s21, 1
	s_mov_b32 s34, 0
	v_lshl_add_u64 v[6:7], s[10:11], 0, v[142:143]
	v_lshl_add_u64 v[4:5], s[10:11], 0, v[140:141]
	s_mov_b64 s[14:15], 0x40000
	v_lshl_add_u64 v[0:1], s[12:13], 0, v[142:143]
	s_cselect_b64 s[16:17], -1, 0
	s_cmp_lg_u32 s21, 1
	v_lshl_add_u64 v[2:3], s[12:13], 0, v[140:141]
	s_cbranch_scc1 .LBB0_908
	s_barrier

.LBB0_911:
	s_add_i32 s61, s61, 1
	s_mov_b32 s63, s8
	s_mul_i32 s8, s61, s33
	s_add_i32 s8, s8, s3
	s_cmpk_lt_i32 s8, 0x108
	s_mov_b32 s62, s47
	s_cselect_b64 s[36:37], -1, 0
	s_mul_i32 s8, s61, s98
	s_add_i32 s8, s8, s99
	s_and_b32 s47, s8, 3
	s_ashr_i32 s8, s8, 2
	s_mov_b64 s[40:41], s[10:11]
	s_and_b64 s[10:11], s[36:37], exec
	s_cselect_b32 s10, s8, s34
	s_cselect_b32 s34, s47, s35
	s_ashr_i32 s11, s10, 31
	s_lshl_b64 s[10:11], s[10:11], 19
	s_mov_b64 s[38:39], s[12:13]
	s_add_u32 s12, s4, s10
	s_addc_u32 s13, s5, s11
	s_and_b64 s[10:11], s[36:37], exec
	s_cselect_b32 s64, s13, s39
	s_cselect_b32 s65, s12, s38
	s_lshl_b32 s10, s34, 19
	s_add_u32 s10, s6, s10
	s_addc_u32 s11, s7, 0
	s_and_b64 s[34:35], s[36:37], exec
	s_cselect_b32 s66, s11, s41
	s_cselect_b32 s67, s10, s40
	s_add_u32 s38, s38, 0x40080
	s_addc_u32 s39, s39, 0
	s_add_u32 s68, s40, 0x100
	v_mov_b32_e32 v0, 0
	s_addc_u32 s69, s41, 0
	s_mov_b32 s70, -2
	v_mov_b32_e32 v1, v0
	v_mov_b32_e32 v2, v0
	v_mov_b32_e32 v3, v0
	v_mov_b32_e32 v4, v0
	v_mov_b32_e32 v5, v0
	v_mov_b32_e32 v6, v0
	v_mov_b32_e32 v7, v0
	v_mov_b32_e32 v8, v0
	v_mov_b32_e32 v9, v0
	v_mov_b32_e32 v10, v0
	v_mov_b32_e32 v11, v0
	v_mov_b32_e32 v16, v0
	v_mov_b32_e32 v17, v0
	v_mov_b32_e32 v18, v0
	v_mov_b32_e32 v19, v0
	v_mov_b32_e32 v24, v0
	v_mov_b32_e32 v25, v0
	v_mov_b32_e32 v26, v0
	s_waitcnt vmcnt(0)
	v_mov_b32_e32 v27, v0
	v_mov_b32_e32 v32, v0
	v_mov_b32_e32 v33, v0
	v_mov_b32_e32 v34, v0
	v_mov_b32_e32 v35, v0
	v_mov_b32_e32 v48, v0
	v_mov_b32_e32 v49, v0
	v_mov_b32_e32 v50, v0
	v_mov_b32_e32 v51, v0
	v_mov_b32_e32 v52, v0
	v_mov_b32_e32 v53, v0
	v_mov_b32_e32 v54, v0
	v_mov_b32_e32 v55, v0
	v_mov_b32_e32 v12, v0
	v_mov_b32_e32 v13, v0
	v_mov_b32_e32 v14, v0
	v_mov_b32_e32 v15, v0
	v_mov_b32_e32 v20, v0
	v_mov_b32_e32 v21, v0
	v_mov_b32_e32 v22, v0
	v_mov_b32_e32 v23, v0
	v_mov_b32_e32 v28, v0
	v_mov_b32_e32 v29, v0
	v_mov_b32_e32 v30, v0
	v_mov_b32_e32 v31, v0
	v_mov_b32_e32 v36, v0
	v_mov_b32_e32 v37, v0
	v_mov_b32_e32 v38, v0
	v_mov_b32_e32 v39, v0
	v_mov_b32_e32 v40, v0
	v_mov_b32_e32 v41, v0
	v_mov_b32_e32 v42, v0
	v_mov_b32_e32 v43, v0
	v_mov_b32_e32 v44, v0
	v_mov_b32_e32 v45, v0
	v_mov_b32_e32 v46, v0
	v_mov_b32_e32 v47, v0
	v_mov_b32_e32 v56, v0
	v_mov_b32_e32 v57, v0
	v_mov_b32_e32 v58, v0
	v_mov_b32_e32 v59, v0
	v_mov_b32_e32 v60, v0
	v_mov_b32_e32 v61, v0
	v_mov_b32_e32 v62, v0
	v_mov_b32_e32 v63, v0
	v_mov_b32_e32 v64, v0
	v_mov_b32_e32 v65, v0
	v_mov_b32_e32 v66, v0
	v_mov_b32_e32 v67, v0
	v_mov_b32_e32 v68, v0
	v_mov_b32_e32 v69, v0
	v_mov_b32_e32 v70, v0
	v_mov_b32_e32 v71, v0
	v_mov_b32_e32 v80, v0
	v_mov_b32_e32 v81, v0
	v_mov_b32_e32 v82, v0
	v_mov_b32_e32 v83, v0
	v_mov_b32_e32 v84, v0
	v_mov_b32_e32 v85, v0
	v_mov_b32_e32 v86, v0
	v_mov_b32_e32 v87, v0
	v_mov_b32_e32 v96, v0
	v_mov_b32_e32 v97, v0
	v_mov_b32_e32 v98, v0
	v_mov_b32_e32 v99, v0
	v_mov_b32_e32 v100, v0
	v_mov_b32_e32 v101, v0
	v_mov_b32_e32 v102, v0
	v_mov_b32_e32 v103, v0
	v_mov_b32_e32 v108, v0
	v_mov_b32_e32 v109, v0
	v_mov_b32_e32 v110, v0
	v_mov_b32_e32 v111, v0
	v_mov_b32_e32 v116, v0
	v_mov_b32_e32 v117, v0
	v_mov_b32_e32 v118, v0
	v_mov_b32_e32 v119, v0
	v_mov_b32_e32 v72, v0
	v_mov_b32_e32 v73, v0
	v_mov_b32_e32 v74, v0
	v_mov_b32_e32 v75, v0
	v_mov_b32_e32 v76, v0
	v_mov_b32_e32 v77, v0
	v_mov_b32_e32 v78, v0
	v_mov_b32_e32 v79, v0
	v_mov_b32_e32 v88, v0
	v_mov_b32_e32 v89, v0
	v_mov_b32_e32 v90, v0
	v_mov_b32_e32 v91, v0
	v_mov_b32_e32 v92, v0
	v_mov_b32_e32 v93, v0
	v_mov_b32_e32 v94, v0
	v_mov_b32_e32 v95, v0
	v_mov_b32_e32 v104, v0
	v_mov_b32_e32 v105, v0
	v_mov_b32_e32 v106, v0
	v_mov_b32_e32 v107, v0
	v_mov_b32_e32 v112, v0
	v_mov_b32_e32 v113, v0
	v_mov_b32_e32 v114, v0
	v_mov_b32_e32 v115, v0
	v_mov_b32_e32 v120, v0
	v_mov_b32_e32 v121, v0
	v_mov_b32_e32 v122, v0
	v_mov_b32_e32 v123, v0
	v_mov_b32_e32 v124, v0
	v_mov_b32_e32 v125, v0
	v_mov_b32_e32 v126, v0
	v_mov_b32_e32 v127, v0

	.amdhsa_kernel _Z4mega6Paramsii
		.amdhsa_group_segment_fixed_size 0
		.amdhsa_private_segment_fixed_size 0
		.amdhsa_kernarg_size 544
		.amdhsa_user_sgpr_count 2
		.amdhsa_user_sgpr_dispatch_ptr 0
		.amdhsa_user_sgpr_queue_ptr 0
		.amdhsa_user_sgpr_kernarg_segment_ptr 1
		.amdhsa_user_sgpr_dispatch_id 0
		.amdhsa_user_sgpr_kernarg_preload_length 0
		.amdhsa_user_sgpr_kernarg_preload_offset 0
		.amdhsa_user_sgpr_private_segment_size 0
		.amdhsa_uses_dynamic_stack 0
		.amdhsa_enable_private_segment 0
		.amdhsa_system_sgpr_workgroup_id_x 1
		.amdhsa_system_sgpr_workgroup_id_y 0
		.amdhsa_system_sgpr_workgroup_id_z 0
		.amdhsa_system_sgpr_workgroup_info 0
		.amdhsa_system_vgpr_workitem_id 2
		.amdhsa_next_free_vgpr 231
		.amdhsa_next_free_sgpr 102
		.amdhsa_accum_offset 232
		.amdhsa_reserve_vcc 1
		.amdhsa_float_round_mode_32 0
		.amdhsa_float_round_mode_16_64 0
		.amdhsa_float_denorm_mode_32 3
		.amdhsa_float_denorm_mode_16_64 3
		.amdhsa_dx10_clamp 1
		.amdhsa_ieee_mode 1
		.amdhsa_fp16_overflow 0
		.amdhsa_tg_split 0
		.amdhsa_exception_fp_ieee_invalid_op 0
		.amdhsa_exception_fp_denorm_src 0
		.amdhsa_exception_fp_ieee_div_zero 0
		.amdhsa_exception_fp_ieee_overflow 0
		.amdhsa_exception_fp_ieee_underflow 0
		.amdhsa_exception_fp_ieee_inexact 0
		.amdhsa_exception_int_div_zero 0
	.end_amdhsa_kernel
